# grid barrier: non-leader workgroups poll the cross-XCD release word directly (one hop less) on top of the unit-drain removal
# speedup vs baseline: 1.0305x; 1.0012x over previous
; __device__ __forceinline__ unsigned xb_ld(unsigned* p)              { return __hip_atomic_load(p, __ATOMIC_RELAXED, __HIP_MEMORY_SCOPE_AGENT); }
; __device__ __forceinline__ unsigned xb_add(unsigned* p, unsigned v) { return __hip_atomic_fetch_add(p, v, __ATOMIC_RELAXED, __HIP_MEMORY_SCOPE_AGENT); }
; #define XB_SPIN(cond, bar) do { unsigned _sp = 0; while (cond) { __builtin_amdgcn_s_sleep(1); \
;     if ((++_sp & 255u) == 0u) { if (xb_ld(&(bar)[XB_TMO])) break; if (_sp > XB_SPIN_CAP) { atomicAdd(&(bar)[XB_TMO], 1u); break; } } } } while (0)
; __device__ __forceinline__ void xcd_barrier(const XcdBarrier& b) {
;     ...
;         const unsigned old = xb_add(&bar[XB_XSUB(b.x)], 1u);
;         const unsigned gen = old / nloc;
;         if (old + 1u == (gen + 1u) * nloc) {
;             __builtin_amdgcn_fence(__ATOMIC_RELEASE, "agent");
;             asm volatile("s_waitcnt vmcnt(0)" ::: "memory");
;             const unsigned og = xb_add(&bar[XB_TOP], 1u);
;             const unsigned tg = og / nx;
;             if (og + 1u == (tg + 1u) * nx) xb_add(&bar[XB_TOPGEN], 1u);
;             else XB_SPIN(xb_ld(&bar[XB_TOPGEN]) == tg, bar);
;             __builtin_amdgcn_fence(__ATOMIC_ACQUIRE, "agent");
;             xb_add(&bar[XB_XGEN(b.x)], 1u);
;             asm volatile("s_waitcnt vmcnt(0)" ::: "memory");
;         } else {
;             XB_SPIN(xb_ld(&bar[XB_XGEN(b.x)]) == gen, bar);
;             __builtin_amdgcn_fence(__ATOMIC_ACQUIRE, "agent");
;             asm volatile("s_waitcnt vmcnt(0)" ::: "memory");
;         }
.LBB0_40:
	s_or_b64 exec, exec, s[6:7]
	v_cvt_f32_u32_e32 v5, v3
	s_waitcnt vmcnt(0)
	v_readfirstlane_b32 s4, v4
	v_sub_u32_e32 v4, 0, v3
	v_rcp_iflag_f32_e32 v5, v5
	v_add_u32_e32 v6, s4, v2
	v_mul_f32_e32 v5, 0x4f7ffffe, v5
	v_cvt_u32_f32_e32 v5, v5
	v_mul_lo_u32 v2, v4, v5
	v_mul_hi_u32 v2, v5, v2
	v_add_u32_e32 v2, v5, v2
	v_mul_hi_u32 v2, v6, v2
	v_mul_lo_u32 v4, v2, v3
	v_sub_u32_e32 v4, v6, v4
	v_add_u32_e32 v5, 1, v2
	v_sub_u32_e32 v7, v4, v3
	v_cmp_ge_u32_e32 vcc, v4, v3
	s_nop 1
	v_cndmask_b32_e32 v2, v2, v5, vcc
	v_cndmask_b32_e32 v4, v4, v7, vcc
	v_add_u32_e32 v5, 1, v2
	v_cmp_ge_u32_e32 vcc, v4, v3
	v_add_u32_e32 v4, 1, v6
	s_nop 0
	v_cndmask_b32_e32 v2, v2, v5, vcc
	v_mul_lo_u32 v5, v3, v2
	v_add_u32_e32 v3, v5, v3
	v_cmp_ne_u32_e32 vcc, v4, v3
	s_and_saveexec_b64 s[4:5], vcc
	s_xor_b64 s[4:5], exec, s[4:5]
	s_cbranch_execz .LBB0_54
	s_waitcnt lgkmcnt(0)
	v_readlane_b32 s8, v254, 45
	v_readlane_b32 s9, v254, 46
	s_nop 4
	global_load_dword v0, v1, s[8:9] sc1
	s_waitcnt vmcnt(0)
	v_cmp_eq_u32_e32 vcc, v0, v2
	s_and_saveexec_b64 s[6:7], vcc
	s_cbranch_execz .LBB0_53
	s_mov_b32 s20, 1
	s_mov_b64 s[10:11], 0
	s_branch .LBB0_44
